# on top of the pipelined weight conversion: s5_kc inner reduction loop unrolled 4x by hand (24 loads in flight per trip, same f32 arithmetic and order)
# speedup vs baseline: 1.0173x; 1.0024x over previous
; DEVI int otid() { int t = threadIdx.x; asm volatile("" : "+v"(t)); return t; }
; DEVI void s5_kc(const Params& p) {
;     ...
;     for (int e = lo + w * 512 + otid(); e < hi; e += (gridDim.x - G2) * 512 * (busy ? 0 : 1) + G2 * 512 * (busy ? 1 : 0)) { const int h2 = e & 15, hh = (e >> 4) & 15, tau = (e >> 8) & 31, g = e >> 13; float s = 0.f;
;         for (int pp = 0; pp < 64; ++pp) { const size_t gp = (size_t)g * 64 + pp; const float ar = apow[(gp * 34 + tau) * 2], ai = apow[(gp * 34 + tau) * 2 + 1];
;             const float br = bb[(gp * 16 + h2) * 2], bi = bb[(gp * 16 + h2) * 2 + 1]; const float cr = p.in[23][((size_t)g * 16 + hh) * 64 + pp], ci = p.in[24][((size_t)g * 16 + hh) * 64 + pp];
;             const float xr = ar * br - ai * bi, xi = ar * bi + ai * br; s += cr * xr - ci * xi; }
;         kc[e] = s; }
.LBB0_199:
	v_lshl_add_u64 v[16:17], s[20:21], 0, v[2:3]
	v_add_co_u32_e32 v16, vcc, 0x1d9c0000, v16
	v_lshl_add_u64 v[14:15], s[20:21], 0, v[4:5]
	s_nop 0
	v_addc_co_u32_e32 v17, vcc, 0, v17, vcc
	v_add_co_u32_e32 v14, vcc, 0x1d880000, v14
	v_lshl_add_u64 v[18:19], v[6:7], 0, s[12:13]
	v_lshl_add_u64 v[20:21], v[8:9], 0, s[12:13]
	s_nop 0
	v_addc_co_u32_e32 v15, vcc, 0, v15, vcc
	global_load_dwordx2 v[56:57], v[18:19], off
	global_load_dwordx2 v[58:59], v[16:17], off
	global_load_dwordx2 v[60:61], v[16:17], off offset:128
	global_load_dwordx2 v[62:63], v[14:15], off
	global_load_dwordx2 v[64:65], v[14:15], off offset:272
	global_load_dwordx2 v[66:67], v[20:21], off
	global_load_dwordx2 v[68:69], v[18:19], off offset:8
	global_load_dwordx2 v[70:71], v[16:17], off offset:256
	global_load_dwordx2 v[72:73], v[16:17], off offset:384
	global_load_dwordx2 v[74:75], v[14:15], off offset:544
	global_load_dwordx2 v[76:77], v[14:15], off offset:816
	global_load_dwordx2 v[78:79], v[20:21], off offset:8
	global_load_dwordx2 v[100:101], v[18:19], off offset:16
	global_load_dwordx2 v[102:103], v[16:17], off offset:512
	global_load_dwordx2 v[104:105], v[16:17], off offset:640
	global_load_dwordx2 v[106:107], v[14:15], off offset:1088
	global_load_dwordx2 v[108:109], v[14:15], off offset:1360
	global_load_dwordx2 v[110:111], v[20:21], off offset:16
	global_load_dwordx2 v[112:113], v[18:19], off offset:24
	global_load_dwordx2 v[114:115], v[16:17], off offset:768
	global_load_dwordx2 v[116:117], v[16:17], off offset:896
	global_load_dwordx2 v[118:119], v[14:15], off offset:1632
	global_load_dwordx2 v[120:121], v[14:15], off offset:1904
	global_load_dwordx2 v[122:123], v[20:21], off offset:24
	s_add_u32 s12, s12, 32
	s_addc_u32 s13, s13, 0
	v_lshl_add_u64 v[2:3], v[2:3], 0, s[8:9]
	v_lshl_add_u64 v[2:3], v[2:3], 0, s[8:9]
	v_lshl_add_u64 v[2:3], v[2:3], 0, s[8:9]
	v_lshl_add_u64 v[2:3], v[2:3], 0, s[8:9]
	v_lshl_add_u64 v[4:5], v[4:5], 0, s[10:11]
	v_lshl_add_u64 v[4:5], v[4:5], 0, s[10:11]
	v_lshl_add_u64 v[4:5], v[4:5], 0, s[10:11]
	v_lshl_add_u64 v[4:5], v[4:5], 0, s[10:11]
	s_waitcnt vmcnt(18)
	v_mov_b32_e32 v26, v56
	v_mov_b32_e32 v27, v66
	v_mov_b32_e32 v28, v57
	v_mov_b32_e32 v29, v67
	v_pk_mul_f32 v[124:125], v[62:63], v[58:59] op_sel:[1,1] op_sel_hi:[0,1]
	v_pk_mul_f32 v[126:127], v[64:65], v[60:61] op_sel:[1,1] op_sel_hi:[0,1]
	v_pk_fma_f32 v[128:129], v[62:63], v[58:59], v[124:125] neg_lo:[0,0,1] neg_hi:[0,0,1]
	v_pk_fma_f32 v[124:125], v[62:63], v[58:59], v[124:125] op_sel_hi:[1,0,1]
	v_pk_fma_f32 v[130:131], v[64:65], v[60:61], v[126:127] neg_lo:[0,0,1] neg_hi:[0,0,1]
	v_pk_fma_f32 v[126:127], v[64:65], v[60:61], v[126:127] op_sel_hi:[1,0,1]
	v_mov_b32_e32 v129, v125
	v_mov_b32_e32 v131, v127
	v_pk_mul_f32 v[124:125], v[26:27], v[128:129]
	v_pk_mul_f32 v[126:127], v[28:29], v[130:131]
	v_sub_f32_e32 v1, v124, v125
	v_sub_f32_e32 v13, v126, v127
	v_add_f32_e32 v1, v12, v1
	v_add_f32_e32 v12, v1, v13
	s_waitcnt vmcnt(12)
	v_mov_b32_e32 v26, v68
	v_mov_b32_e32 v27, v78
	v_mov_b32_e32 v28, v69
	v_mov_b32_e32 v29, v79
	v_pk_mul_f32 v[124:125], v[74:75], v[70:71] op_sel:[1,1] op_sel_hi:[0,1]
	v_pk_mul_f32 v[126:127], v[76:77], v[72:73] op_sel:[1,1] op_sel_hi:[0,1]
	v_pk_fma_f32 v[128:129], v[74:75], v[70:71], v[124:125] neg_lo:[0,0,1] neg_hi:[0,0,1]
	v_pk_fma_f32 v[124:125], v[74:75], v[70:71], v[124:125] op_sel_hi:[1,0,1]
	v_pk_fma_f32 v[130:131], v[76:77], v[72:73], v[126:127] neg_lo:[0,0,1] neg_hi:[0,0,1]
	v_pk_fma_f32 v[126:127], v[76:77], v[72:73], v[126:127] op_sel_hi:[1,0,1]
	v_mov_b32_e32 v129, v125
	v_mov_b32_e32 v131, v127
	v_pk_mul_f32 v[124:125], v[26:27], v[128:129]
	v_pk_mul_f32 v[126:127], v[28:29], v[130:131]
	v_sub_f32_e32 v1, v124, v125
	v_sub_f32_e32 v13, v126, v127
	v_add_f32_e32 v1, v12, v1
	v_add_f32_e32 v12, v1, v13
	s_waitcnt vmcnt(6)
	v_mov_b32_e32 v26, v100
	v_mov_b32_e32 v27, v110
	v_mov_b32_e32 v28, v101
	v_mov_b32_e32 v29, v111
	v_pk_mul_f32 v[124:125], v[106:107], v[102:103] op_sel:[1,1] op_sel_hi:[0,1]
	v_pk_mul_f32 v[126:127], v[108:109], v[104:105] op_sel:[1,1] op_sel_hi:[0,1]
	v_pk_fma_f32 v[128:129], v[106:107], v[102:103], v[124:125] neg_lo:[0,0,1] neg_hi:[0,0,1]
	v_pk_fma_f32 v[124:125], v[106:107], v[102:103], v[124:125] op_sel_hi:[1,0,1]
	v_pk_fma_f32 v[130:131], v[108:109], v[104:105], v[126:127] neg_lo:[0,0,1] neg_hi:[0,0,1]
	v_pk_fma_f32 v[126:127], v[108:109], v[104:105], v[126:127] op_sel_hi:[1,0,1]
	v_mov_b32_e32 v129, v125
	v_mov_b32_e32 v131, v127
	v_pk_mul_f32 v[124:125], v[26:27], v[128:129]
	v_pk_mul_f32 v[126:127], v[28:29], v[130:131]
	v_sub_f32_e32 v1, v124, v125
	v_sub_f32_e32 v13, v126, v127
	v_add_f32_e32 v1, v12, v1
	v_add_f32_e32 v12, v1, v13
	s_waitcnt vmcnt(0)
	v_mov_b32_e32 v26, v112
	v_mov_b32_e32 v27, v122
	v_mov_b32_e32 v28, v113
	v_mov_b32_e32 v29, v123
	v_pk_mul_f32 v[124:125], v[118:119], v[114:115] op_sel:[1,1] op_sel_hi:[0,1]
	v_pk_mul_f32 v[126:127], v[120:121], v[116:117] op_sel:[1,1] op_sel_hi:[0,1]
	v_pk_fma_f32 v[128:129], v[118:119], v[114:115], v[124:125] neg_lo:[0,0,1] neg_hi:[0,0,1]
	v_pk_fma_f32 v[124:125], v[118:119], v[114:115], v[124:125] op_sel_hi:[1,0,1]
	v_pk_fma_f32 v[130:131], v[120:121], v[116:117], v[126:127] neg_lo:[0,0,1] neg_hi:[0,0,1]
	v_pk_fma_f32 v[126:127], v[120:121], v[116:117], v[126:127] op_sel_hi:[1,0,1]
	v_mov_b32_e32 v129, v125
	v_mov_b32_e32 v131, v127
	v_pk_mul_f32 v[124:125], v[26:27], v[128:129]
	v_pk_mul_f32 v[126:127], v[28:29], v[130:131]
	v_sub_f32_e32 v1, v124, v125
	v_sub_f32_e32 v13, v126, v127
	v_add_f32_e32 v1, v12, v1
	v_add_f32_e32 v12, v1, v13
	s_cmpk_eq_i32 s12, 0x100
	s_cbranch_scc0 .LBB0_199
	v_readlane_b32 s2, v252, 40
	v_ashrrev_i32_e32 v1, 31, v0
	v_readlane_b32 s3, v252, 41
	v_add_u32_e32 v10, s16, v10
	v_add_u32_e32 v11, s17, v11
	v_lshl_add_u64 v[2:3], v[0:1], 2, s[2:3]
	v_add_u32_e32 v0, s15, v0
	v_cmp_le_i32_e32 vcc, s14, v0
	s_or_b64 s[4:5], vcc, s[4:5]
	global_store_dword v[2:3], v12, off
	s_andn2_b64 exec, exec, s[4:5]
	s_cbranch_execnz .LBB0_198
